# HGRN c1: V^T staging lane mapping spreads LDS banks (same remap as c3)
# speedup vs baseline: 1.0125x; 1.0080x over previous
; DEV int hg_row0(int cidx, int b) { return (cidx < 4) ? (MM + b * 256 + cidx * 64) : (b * 8192 + (cidx - 4) * 64); }
; DEV void phase_hg_c1(const Params& p, char* smem) {
;     ...
;     const int cidx = item >> 4, bh = item & 15, b = bh >> 3, h = bh & 7;
;     const int r0 = hg_row0(cidx, b);
;     __syncthreads();
; #pragma unroll
;     for (int i = 0; i < 4; i++) {
;       int id = tid + i * 256; int s = id >> 4, cc = id & 15;
;       uint4 u = *(const uint4*)(IH + (size_t)(r0 + s) * 1024 + h * 128 + cc * 8);
;       uint4 lf = *(const uint4*)(LFp + (size_t)(r0 + s) * 1024 + h * 128 + cc * 8);
;       *(uint4*)(RB + s * 144 + cc * 8) = lf;
;       bf16_t* vt = Vt + (cc * 8) * 80 + s;
;       vt[0] = (bf16_t)(u.x & 0xffff); vt[80] = (bf16_t)(u.x >> 16); vt[160] = (bf16_t)(u.y & 0xffff); vt[240] = (bf16_t)(u.y >> 16);
;       vt[320] = (bf16_t)(u.z & 0xffff); vt[400] = (bf16_t)(u.z >> 16); vt[480] = (bf16_t)(u.w & 0xffff); vt[560] = (bf16_t)(u.w >> 16);
;     }
.LBB0_305:
	s_ashr_i32 s11, s10, 4
	s_and_b32 s0, s10, 15
	s_bfe_u32 s1, s10, 0x10003
	s_lshl_b32 s2, s11, 6
	s_cmp_lt_i32 s11, 4
	s_movk_i32 s6, 0xff00
	s_cselect_b32 s3, 8, 13
	s_cselect_b32 s6, 0x4000, s6
	s_lshl_b32 s1, s1, s3
	s_add_i32 s2, s6, s2
	s_add_i32 s1, s2, s1
	s_lshl_b32 s2, s10, 8
	v_add_u32_e32 v22, s1, v36
	s_and_b32 s52, s2, 0x700
	v_ashrrev_i32_e32 v23, 31, v22
	v_lshl_add_u64 v[58:59], v[4:5], 0, s[52:53]
	v_lshl_add_u64 v[60:61], v[6:7], 0, s[52:53]
	v_bfe_u32 v160, v195, 2, 4
	v_lshrrev_b32_e32 v161, 6, v195
	v_and_b32_e32 v166, 3, v195
	v_lshl_or_b32 v161, v161, 2, v166
	v_lshrrev_b32_e32 v166, 4, v195
	v_sub_u32_e32 v160, v160, v166
	v_and_b32_e32 v166, 15, v195
	v_sub_u32_e32 v161, v161, v166
	v_lshlrev_b32_e32 v162, 11, v160
	v_lshl_add_u32 v162, v161, 4, v162
	v_ashrrev_i32_e32 v163, 31, v162
	v_mul_i32_i24_e32 v164, 0x500, v161
	v_lshl_add_u32 v164, v160, 1, v164
	v_lshlrev_b64 v[22:23], 11, v[22:23]
	v_lshl_add_u64 v[24:25], v[58:59], 0, v[22:23]
	v_lshl_add_u64 v[28:29], v[60:61], 0, v[22:23]
	s_waitcnt lgkmcnt(0)
	s_barrier
	v_lshl_add_u64 v[24:25], v[24:25], 0, v[162:163]
	global_load_dwordx4 v[24:27], v[24:25], off
	v_add_u32_e32 v17, v2, v37
	global_load_dwordx4 v[28:31], v[28:29], off
	s_lshl_b32 s12, s0, 1
	s_cmp_gt_i32 s11, 3
	s_cselect_b32 s0, 0x87, 3
	s_sub_i32 s13, s0, s11
	s_mov_b32 s14, 0
	s_mov_b64 s[6:7], -1
	s_waitcnt vmcnt(0)
	ds_write_b128 v17, v[28:31] offset:20480
	v_add_u32_e32 v165, v38, v164
	ds_write_b16 v165, v24 offset:40960
	ds_write_b16_d16_hi v165, v24 offset:41120
	ds_write_b16 v165, v25 offset:41280
	ds_write_b16_d16_hi v165, v25 offset:41440
	ds_write_b16 v165, v26 offset:41600
	ds_write_b16_d16_hi v165, v26 offset:41760
	ds_write_b16 v165, v27 offset:41920
	ds_write_b16_d16_hi v165, v27 offset:42080
	v_add_u32_e32 v24, s1, v39
	v_ashrrev_i32_e32 v25, 31, v24
	v_lshlrev_b64 v[24:25], 11, v[24:25]
	v_lshl_add_u64 v[26:27], v[58:59], 0, v[24:25]
	v_lshl_add_u64 v[30:31], v[60:61], 0, v[24:25]
	v_lshl_add_u64 v[26:27], v[26:27], 0, v[162:163]
	global_load_dwordx4 v[26:29], v[26:27], off
	v_add_u32_e32 v17, v2, v40
	global_load_dwordx4 v[54:57], v[30:31], off
	s_waitcnt vmcnt(0)
	ds_write_b128 v17, v[54:57] offset:20480
	v_add_u32_e32 v165, v41, v164
	ds_write_b16 v165, v26 offset:40960
	ds_write_b16_d16_hi v165, v26 offset:41120
	ds_write_b16 v165, v27 offset:41280
	ds_write_b16_d16_hi v165, v27 offset:41440
	ds_write_b16 v165, v28 offset:41600
	ds_write_b16_d16_hi v165, v28 offset:41760
	ds_write_b16 v165, v29 offset:41920
	ds_write_b16_d16_hi v165, v29 offset:42080
	v_add_u32_e32 v26, s1, v42
	v_ashrrev_i32_e32 v27, 31, v26
	v_lshlrev_b64 v[26:27], 11, v[26:27]
	v_lshl_add_u64 v[28:29], v[58:59], 0, v[26:27]
	v_lshl_add_u64 v[54:55], v[60:61], 0, v[26:27]
	v_lshl_add_u64 v[28:29], v[28:29], 0, v[162:163]
	global_load_dwordx4 v[28:31], v[28:29], off
	v_add_u32_e32 v17, v2, v43
	global_load_dwordx4 v[54:57], v[54:55], off
	s_waitcnt vmcnt(0)
	ds_write_b128 v17, v[54:57] offset:20480
	v_add_u32_e32 v165, v44, v164
	ds_write_b16 v165, v28 offset:40960
	ds_write_b16_d16_hi v165, v28 offset:41120
	ds_write_b16 v165, v29 offset:41280
	ds_write_b16_d16_hi v165, v29 offset:41440
	ds_write_b16 v165, v30 offset:41600
	ds_write_b16_d16_hi v165, v30 offset:41760
	ds_write_b16 v165, v31 offset:41920
	ds_write_b16_d16_hi v165, v31 offset:42080
	v_add_u32_e32 v28, s1, v45
	v_ashrrev_i32_e32 v29, 31, v28
	v_lshlrev_b64 v[62:63], 11, v[28:29]
	v_lshl_add_u64 v[28:29], v[58:59], 0, v[62:63]
	v_lshl_add_u64 v[54:55], v[60:61], 0, v[62:63]
	v_lshl_add_u64 v[28:29], v[28:29], 0, v[162:163]
	global_load_dwordx4 v[28:31], v[28:29], off
	v_add_u32_e32 v17, v2, v46
	global_load_dwordx4 v[54:57], v[54:55], off
	s_mov_b64 s[0:1], 0
	s_waitcnt vmcnt(0)
	ds_write_b128 v17, v[54:57] offset:20480
	v_add_u32_e32 v165, v47, v164
	ds_write_b16 v165, v28 offset:40960
	ds_write_b16_d16_hi v165, v28 offset:41120
	ds_write_b16 v165, v29 offset:41280
	ds_write_b16_d16_hi v165, v29 offset:41440
	ds_write_b16 v165, v30 offset:41600
	ds_write_b16_d16_hi v165, v30 offset:41760
	ds_write_b16 v165, v31 offset:41920
	ds_write_b16_d16_hi v165, v31 offset:42080
	v_lshl_add_u64 v[28:29], v[12:13], 0, s[52:53]
	v_lshl_add_u64 v[22:23], v[28:29], 0, v[22:23]
	v_lshl_add_u64 v[24:25], v[28:29], 0, v[24:25]
	v_lshl_add_u64 v[26:27], v[28:29], 0, v[26:27]
	v_lshl_add_u64 v[28:29], v[28:29], 0, v[62:63]
	s_branch .LBB0_307
